# layer-0 up-projection weight transposes moved from phase 0 into the idle time of phase 2's two-unit workgroups (copied item loop, SGPRs saved in spare VGPR lanes)
# speedup vs baseline: 1.0492x; 1.0016x over previous
.LBB0_622:
	s_lshl_b32 s20, s20, 5
	s_and_b32 s38, s20, 0x60
	s_lshl_b32 s1, s3, 13
	s_lshl_b32 s39, s38, 7
	s_and_b64 s[20:21], s[36:37], exec
	s_cselect_b32 s20, 0x8400, 0
	s_add_u32 s22, s68, s20
	s_addc_u32 s23, s69, 0
	s_and_b64 s[20:21], s[36:37], exec
	s_cselect_b32 s20, 0x2c00, 0
	s_add_u32 s46, s70, s20
	s_addc_u32 s47, s71, 0
	s_add_u32 s48, s22, 0x2c00
	s_addc_u32 s49, s23, 0
	s_add_u32 s50, s22, 0x5800
	s_addc_u32 s51, s23, 0
	s_add_i32 m0, s35, 0x18000
	v_lshl_add_u64 v[4:5], v[4:5], 0, s[28:29]
	s_waitcnt vmcnt(2)
	s_barrier
	global_load_lds_dwordx4 v[4:5], off
	v_lshl_add_u64 v[2:3], v[2:3], 0, s[28:29]
	s_add_i32 m0, s35, 0x1a000
	s_add_i32 s56, s35, 0x8000
	s_add_i32 s57, s35, 0xa000
	global_load_lds_dwordx4 v[2:3], off
	v_lshl_add_u64 v[0:1], v[0:1], 0, s[28:29]
	s_mov_b32 m0, s56
	s_add_u32 s20, s62, 0x40080
	global_load_lds_dwordx4 v[0:1], off
	v_lshl_add_u64 v[0:1], v[6:7], 0, s[28:29]
	s_mov_b32 m0, s57
	s_addc_u32 s21, s63, 0
	global_load_lds_dwordx4 v[0:1], off
	s_add_i32 m0, s35, 0x1c000
	v_lshl_add_u64 v[0:1], s[20:21], 0, v[196:197]
	global_load_lds_dwordx4 v[0:1], off
	v_lshl_add_u64 v[0:1], s[20:21], 0, v[200:201]
	s_add_i32 m0, s35, 0x1e000
	v_and_b32_e32 v193, 15, v192
	global_load_lds_dwordx4 v[0:1], off
	s_cmpk_lt_u32 s2, 0x100
	s_cselect_b64 s[52:53], -1, 0
	v_cmp_gt_u32_e32 vcc, 2, v193
	v_lshrrev_b32_e32 v0, 1, v192
	s_and_b64 s[20:21], s[52:53], vcc
	v_and_b32_e32 v0, 24, v0
	v_writelane_b32 v255, s20, 10
	v_lshlrev_b32_e32 v1, 1, v0
	v_lshlrev_b32_e32 v2, 2, v192
	v_writelane_b32 v255, s21, 11
	v_cmp_eq_u32_e64 s[20:21], 0, v193
	v_lshl_or_b32 v1, v193, 6, v1
	v_and_b32_e32 v2, 32, v2
	v_writelane_b32 v255, s20, 20
	v_bitop3_b32 v3, v1, s1, v2 bitop3:0xde
	s_lshl_b32 s1, s3, 10
	v_writelane_b32 v255, s21, 21
	v_or_b32_e32 v211, s38, v0
	s_add_i32 s1, s1, 0
	v_readlane_b32 s20, v255, 12
	v_lshlrev_b32_e32 v0, 2, v211
	s_add_i32 s2, s1, 0x20000
	v_cmp_lt_u32_e32 vcc, 13, v193
	v_readlane_b32 s21, v255, 13
	v_add_u32_e32 v212, s2, v0
	s_add_i32 s2, s1, 0x20800
	s_and_b64 s[20:21], s[20:21], vcc
	s_cmp_gt_i32 s3, 0
	s_cselect_b64 s[82:83], -1, 0
	s_cmp_lt_i32 s3, 3
	v_add_u32_e32 v225, s2, v0
	s_cselect_b64 s[84:85], -1, 0
	s_add_i32 s2, s1, 0x1fe00
	s_cmp_gt_i32 s3, -2
	s_cselect_b64 s[86:87], -1, 0
	s_cmp_lt_i32 s3, 1
	s_cselect_b64 s[88:89], -1, 0
	s_add_i32 s1, s1, 0x20600
	v_add_u32_e32 v228, s2, v0
	v_add_u32_e32 v229, s1, v0
	v_lshlrev_b32_e32 v0, 14, v8
	v_and_b32_e32 v0, 0xffff8000, v0
	v_bitop3_b32 v210, s39, v1, v2 bitop3:0xf6
	v_lshl_add_u32 v0, v9, 11, v0
	v_and_b32_e32 v1, 1, v8
	v_writelane_b32 v255, s20, 14
	v_lshl_or_b32 v0, v1, 6, v0
	v_lshl_add_u32 v204, v10, 1, v0
	v_writelane_b32 v255, s21, 15
	v_cmp_eq_u32_e64 s[20:21], 15, v193
	v_lshlrev_b32_e32 v0, 14, v11
	v_and_b32_e32 v0, 0xffff8000, v0
	v_writelane_b32 v255, s20, 22
	s_waitcnt vmcnt(6)
	v_lshl_add_u32 v0, v12, 11, v0
	v_and_b32_e32 v1, 1, v11
	v_writelane_b32 v255, s21, 23
	v_lshl_or_b32 v0, v1, 6, v0
	v_readlane_b32 s1, v255, 6
	v_lshl_or_b32 v203, s3, 6, v193
	s_mov_b32 s80, 0
	v_add_u32_e32 v213, 0x200, v212
	v_add_u32_e32 v226, 0x200, v225
	v_add_u32_e32 v227, 0x800, v212
	v_mul_u32_u24_e32 v202, 0xb00, v193
	s_ashr_i32 s81, s24, 31
	s_ashr_i32 s20, s1, 31
	v_mov_b32_e32 v205, v179
	v_lshl_add_u32 v206, v13, 1, v0
	v_mov_b32_e32 v207, v179
	v_add_u32_e32 v230, 0, v3
	s_barrier
	s_branch .LBB0_625
.Ltr_1148:
	s_branch .LBB0_1148
.LBB0_623:
	s_mov_b64 s[0:1], 0

.LBB0_1113:
	s_lshl_b32 s0, s56, 3
	v_readlane_b32 s1, v255, 5
	s_add_i32 s2, s1, s0
	s_lshl_b32 s20, s24, 3
	s_movk_i32 s99, 0x1300
	s_cmpk_lg_u32 s24, 0x100
	s_cbranch_scc1 .Ltq_b0
	s_movk_i32 s99, 0x800
.Ltq_b0:
	s_cmp_ge_i32 s2, s99
	s_barrier
	s_cbranch_scc1 .LBB0_1125
	s_lshl_b32 s0, s1, 14
	v_and_b32_e32 v0, 7, v192
	s_add_i32 s0, s0, 0
	v_lshlrev_b32_e32 v178, 4, v0
	v_mul_u32_u24_e32 v0, 0x420, v0
	v_lshlrev_b32_e32 v1, 2, v44
	v_add_u32_e32 v12, s0, v178
	v_add3_u32 v17, s0, v0, v1
	v_readlane_b32 s0, v253, 6
	v_readlane_b32 s1, v253, 7
	s_mov_b64 s[60:61], s[84:85]
	v_readlane_b32 s80, v253, 46
	v_lshl_add_u64 v[0:1], s[0:1], 0, v[178:179]
	v_readlane_b32 s0, v254, 18
	v_readlane_b32 s1, v254, 19
	v_readlane_b32 s84, v253, 50
	v_readlane_b32 s85, v253, 51
	v_lshl_add_u64 v[2:3], s[0:1], 0, v[178:179]
	v_readlane_b32 s90, v253, 56
	v_readlane_b32 s91, v253, 57
	s_lshl_b32 s0, s2, 1
	v_mul_u32_u24_e32 v13, 0x84, v44
	v_or_b32_e32 v14, 8, v44
	v_or_b32_e32 v15, 16, v44
	v_or_b32_e32 v16, 24, v44
	v_lshl_add_u64 v[4:5], s[78:79], 0, v[178:179]
	v_lshl_add_u64 v[6:7], s[66:67], 0, v[178:179]
	v_lshl_add_u64 v[8:9], s[90:91], 0, v[178:179]
	v_lshl_add_u64 v[10:11], s[84:85], 0, v[178:179]
	s_lshl_b32 s3, s2, 5
	s_lshl_b32 s21, s20, 5
	s_add_i32 s33, s0, 0x1f400
	s_lshl_b32 s34, s20, 1
	s_mov_b32 s35, s2
	s_mov_b32 s38, 0x10000
	s_movk_i32 s39, 0x3000
	s_mov_b32 s40, 0x2c000
	s_mov_b32 s41, 0x58000
	s_mov_b32 s42, 0x84000
	s_mov_b32 s43, 0xb0000
	s_mov_b32 s56, 0xdc000
	s_mov_b32 s57, 0x108000
	s_mov_b32 s58, 0x134000
	v_readlane_b32 s81, v253, 47
	v_readlane_b32 s82, v253, 48
	v_readlane_b32 s83, v253, 49
	v_readlane_b32 s86, v253, 52
	v_readlane_b32 s87, v253, 53
	v_readlane_b32 s88, v253, 54
	v_readlane_b32 s89, v253, 55
	v_readlane_b32 s92, v253, 58
	v_readlane_b32 s93, v253, 59
	v_readlane_b32 s94, v253, 60
	v_readlane_b32 s95, v253, 61
	s_branch .LBB0_1116
.LBB0_1115:
	s_add_i32 s35, s35, s20
	s_add_i32 s3, s3, s21
	s_add_i32 s33, s33, s34
	s_cmp_lt_i32 s35, s99
	s_cbranch_scc0 .LBB0_1124

.LBB0_1147:
	s_waitcnt vmcnt(0)
	s_cmp_lg_u32 s55, 2
	s_cbranch_scc1 .Ltq_skip
	s_cmpk_lg_u32 s24, 0x100
	s_cbranch_scc1 .Ltq_skip
	v_readlane_b32 s98, v255, 6
	s_nop 3
	s_cmp_lt_u32 s98, 64
	s_cbranch_scc1 .Ltq_skip
	s_barrier
	v_writelane_b32 v255, s0, 24
	v_writelane_b32 v255, s1, 25
	v_writelane_b32 v255, s2, 26
	v_writelane_b32 v255, s3, 27
	v_writelane_b32 v255, s20, 28
	v_writelane_b32 v255, s21, 29
	v_writelane_b32 v255, s22, 30
	v_writelane_b32 v255, s23, 31
	v_writelane_b32 v255, s26, 32
	v_writelane_b32 v255, s33, 33
	v_writelane_b32 v255, s34, 34
	v_writelane_b32 v255, s35, 35
	v_writelane_b32 v255, s36, 36
	v_writelane_b32 v255, s37, 37
	v_writelane_b32 v255, s38, 38
	v_writelane_b32 v255, s39, 39
	v_writelane_b32 v255, s40, 40
	v_writelane_b32 v255, s41, 41
	v_writelane_b32 v255, s42, 42
	v_writelane_b32 v255, s43, 43
	v_writelane_b32 v255, s56, 44
	v_writelane_b32 v255, s57, 45
	v_writelane_b32 v255, s58, 46
	v_writelane_b32 v255, s60, 47
	v_writelane_b32 v255, s61, 48
	v_writelane_b32 v255, s80, 49
	v_writelane_b32 v255, s81, 50
	v_writelane_b32 v255, s82, 51
	v_writelane_b32 v255, s83, 52
	v_writelane_b32 v255, s86, 53
	v_writelane_b32 v255, s87, 54
	v_writelane_b32 v255, s88, 55
	v_writelane_b32 v255, s89, 56
	v_writelane_b32 v255, s90, 57
	v_writelane_b32 v255, s91, 58
	v_writelane_b32 v255, s92, 59
	v_writelane_b32 v255, s93, 60
	v_writelane_b32 v255, s94, 61
	v_writelane_b32 v255, s95, 62
	v_readlane_b32 s1, v255, 5
	s_nop 3
	s_sub_i32 s0, s98, 64
	s_lshl_b32 s0, s0, 3
	s_add_i32 s2, s1, s0
	s_addk_i32 s2, 0x800
	s_movk_i32 s20, 0x600
	s_mov_b32 s27, 0
	v_and_b32_e32 v44, 63, v192
	v_lshrrev_b32_e32 v44, 3, v44
	s_lshl_b32 s0, s1, 14
	v_and_b32_e32 v0, 7, v192
	s_add_i32 s0, s0, 0
	v_lshlrev_b32_e32 v178, 4, v0
	v_mul_u32_u24_e32 v0, 0x420, v0
	v_lshlrev_b32_e32 v1, 2, v44
	v_add_u32_e32 v12, s0, v178
	v_add3_u32 v17, s0, v0, v1
	v_readlane_b32 s0, v253, 6
	v_readlane_b32 s1, v253, 7
	s_mov_b64 s[60:61], s[84:85]
	v_readlane_b32 s80, v253, 46
	v_lshl_add_u64 v[0:1], s[0:1], 0, v[178:179]
	v_readlane_b32 s0, v254, 18
	v_readlane_b32 s1, v254, 19
	v_readlane_b32 s84, v253, 50
	v_readlane_b32 s85, v253, 51
	v_lshl_add_u64 v[2:3], s[0:1], 0, v[178:179]
	v_readlane_b32 s90, v253, 56
	v_readlane_b32 s91, v253, 57
	s_lshl_b32 s0, s2, 1
	v_mul_u32_u24_e32 v13, 0x84, v44
	v_or_b32_e32 v14, 8, v44
	v_or_b32_e32 v15, 16, v44
	v_or_b32_e32 v16, 24, v44
	v_lshl_add_u64 v[4:5], s[78:79], 0, v[178:179]
	v_lshl_add_u64 v[6:7], s[66:67], 0, v[178:179]
	v_lshl_add_u64 v[8:9], s[90:91], 0, v[178:179]
	v_lshl_add_u64 v[10:11], s[84:85], 0, v[178:179]
	s_lshl_b32 s3, s2, 5
	s_lshl_b32 s21, s20, 5
	s_add_i32 s33, s0, 0x1f400
	s_lshl_b32 s34, s20, 1
	s_mov_b32 s35, s2
	s_mov_b32 s38, 0x10000
	s_movk_i32 s39, 0x3000
	s_mov_b32 s40, 0x2c000
	s_mov_b32 s41, 0x58000
	s_mov_b32 s42, 0x84000
	s_mov_b32 s43, 0xb0000
	s_mov_b32 s56, 0xdc000
	s_mov_b32 s57, 0x108000
	s_mov_b32 s58, 0x134000
	v_readlane_b32 s81, v253, 47
	v_readlane_b32 s82, v253, 48
	v_readlane_b32 s83, v253, 49
	v_readlane_b32 s86, v253, 52
	v_readlane_b32 s87, v253, 53
	v_readlane_b32 s88, v253, 54
	v_readlane_b32 s89, v253, 55
	v_readlane_b32 s92, v253, 58
	v_readlane_b32 s93, v253, 59
	v_readlane_b32 s94, v253, 60
	v_readlane_b32 s95, v253, 61
	s_branch .Ltq_1116

.Ltq_exit:
	s_waitcnt vmcnt(0) lgkmcnt(0)
	s_mov_b64 s[84:85], s[60:61]
	v_readlane_b32 s0, v255, 24
	v_readlane_b32 s1, v255, 25
	v_readlane_b32 s2, v255, 26
	v_readlane_b32 s3, v255, 27
	v_readlane_b32 s20, v255, 28
	v_readlane_b32 s21, v255, 29
	v_readlane_b32 s22, v255, 30
	v_readlane_b32 s23, v255, 31
	v_readlane_b32 s26, v255, 32
	v_readlane_b32 s33, v255, 33
	v_readlane_b32 s34, v255, 34
	v_readlane_b32 s35, v255, 35
	v_readlane_b32 s36, v255, 36
	v_readlane_b32 s37, v255, 37
	v_readlane_b32 s38, v255, 38
	v_readlane_b32 s39, v255, 39
	v_readlane_b32 s40, v255, 40
	v_readlane_b32 s41, v255, 41
	v_readlane_b32 s42, v255, 42
	v_readlane_b32 s43, v255, 43
	v_readlane_b32 s56, v255, 44
	v_readlane_b32 s57, v255, 45
	v_readlane_b32 s58, v255, 46
	v_readlane_b32 s60, v255, 47
	v_readlane_b32 s61, v255, 48
	v_readlane_b32 s80, v255, 49
	v_readlane_b32 s81, v255, 50
	v_readlane_b32 s82, v255, 51
	v_readlane_b32 s83, v255, 52
	v_readlane_b32 s86, v255, 53
	v_readlane_b32 s87, v255, 54
	v_readlane_b32 s88, v255, 55
	v_readlane_b32 s89, v255, 56
	v_readlane_b32 s90, v255, 57
	v_readlane_b32 s91, v255, 58
	v_readlane_b32 s92, v255, 59
	v_readlane_b32 s93, v255, 60
	v_readlane_b32 s94, v255, 61
	v_readlane_b32 s95, v255, 62
	s_nop 4
.Ltq_skip:
	v_readlane_b32 s48, v254, 45
	v_readlane_b32 s50, v254, 47
	v_readlane_b32 s52, v254, 49
	v_readlane_b32 s46, v254, 51
	s_barrier
	v_readlane_b32 s90, v255, 7
	v_readlane_b32 s49, v254, 46
	v_readlane_b32 s51, v254, 48
	v_readlane_b32 s53, v254, 50
	v_readlane_b32 s47, v254, 52
	s_movk_i32 s42, 0x210
	s_movk_i32 s43, 0x90
	v_readlane_b32 s56, v255, 6
	s_branch .LBB0_1093
